# GEMM K-loop: six +0x80 LDS-DMA source addresses via the load's immediate offset (M0 compensated by -128) instead of 64-bit VALU adds
# speedup vs baseline: 1.0223x; 1.0020x over previous
.LBB0_760:
	s_add_i32 s38, s46, 2
	s_add_u32 s8, s26, s4
	s_addc_u32 s9, s27, s5
	s_add_u32 s8, s8, 0x100
	s_addc_u32 s9, s9, 0
	s_add_u32 s30, s44, s4
	s_addc_u32 s31, s45, s5
	v_add_u32_e32 v252, 0x10000, v193
	ds_read_b128 v[132:135], v252
	ds_read_b128 v[136:139], v252 offset:1024
	ds_read_b128 v[140:143], v252 offset:2048
	ds_read_b128 v[144:147], v252 offset:3072
	s_cmp_eq_u32 s71, s46
	s_cselect_b32 s9, s13, s9
	s_cselect_b32 s8, s12, s8
	s_cselect_b32 s31, s57, s31
	s_cselect_b32 s30, s56, s30
	v_lshl_add_u64 v[190:191], v[128:129], 0, s[4:5]
	s_add_i32 m0, s19, 0xc000
	ds_read_b128 v[148:151], v202
	ds_read_b128 v[152:155], v202 offset:1024
	ds_read_b128 v[156:159], v202 offset:2048
	ds_read_b128 v[160:163], v202 offset:3072
	ds_read_b128 v[164:167], v202 offset:4096
	ds_read_b128 v[204:207], v202 offset:5120
	ds_read_b128 v[208:211], v202 offset:6144
	ds_read_b128 v[212:215], v202 offset:7168
	global_load_lds_dwordx4 v[190:191], off
	s_add_i32 m0, s19, 0xe000
	v_lshl_add_u64 v[190:191], v[130:131], 0, s[4:5]
	global_load_lds_dwordx4 v[190:191], off
	s_waitcnt lgkmcnt(8)
	s_barrier
	s_waitcnt lgkmcnt(0)
	v_mfma_f32_16x16x32_bf16 v[124:127], v[132:135], v[148:151], v[124:127]
	v_mfma_f32_16x16x32_bf16 v[120:123], v[140:143], v[148:151], v[120:123]
	v_mfma_f32_16x16x32_bf16 v[108:111], v[132:135], v[156:159], v[108:111]
	v_mfma_f32_16x16x32_bf16 v[104:107], v[140:143], v[156:159], v[104:107]
	v_mfma_f32_16x16x32_bf16 v[92:95], v[132:135], v[164:167], v[92:95]
	v_mfma_f32_16x16x32_bf16 v[88:91], v[140:143], v[164:167], v[88:91]
	v_mfma_f32_16x16x32_bf16 v[76:79], v[132:135], v[208:211], v[76:79]
	v_mfma_f32_16x16x32_bf16 v[72:75], v[140:143], v[208:211], v[72:75]
	v_mfma_f32_16x16x32_bf16 v[124:127], v[136:139], v[152:155], v[124:127]
	v_mfma_f32_16x16x32_bf16 v[120:123], v[144:147], v[152:155], v[120:123]
	v_mfma_f32_16x16x32_bf16 v[108:111], v[136:139], v[160:163], v[108:111]
	v_mfma_f32_16x16x32_bf16 v[104:107], v[144:147], v[160:163], v[104:107]
	v_mfma_f32_16x16x32_bf16 v[92:95], v[136:139], v[204:207], v[92:95]
	v_mfma_f32_16x16x32_bf16 v[88:91], v[144:147], v[204:207], v[88:91]
	v_mfma_f32_16x16x32_bf16 v[76:79], v[136:139], v[212:215], v[76:79]
	v_mfma_f32_16x16x32_bf16 v[72:75], v[144:147], v[212:215], v[72:75]
	s_barrier
	s_add_i32 s47, s53, 0x10000
	ds_read_b128 v[216:219], v252 offset:16384
	ds_read_b128 v[220:223], v252 offset:17408
	ds_read_b128 v[232:235], v252 offset:18432
	ds_read_b128 v[240:243], v252 offset:19456
	s_mov_b32 m0, s47
	v_lshl_add_u64 v[190:191], s[30:31], 0, v[180:181]
	global_load_lds_dwordx4 v[190:191], off
	s_add_i32 m0, s47, 0x2000
	v_lshl_add_u64 v[224:225], s[30:31], 0, v[176:177]
	global_load_lds_dwordx4 v[224:225], off
	s_barrier
	s_waitcnt lgkmcnt(0)
	v_mfma_f32_16x16x32_bf16 v[116:119], v[216:219], v[148:151], v[116:119]
	v_mfma_f32_16x16x32_bf16 v[112:115], v[232:235], v[148:151], v[112:115]
	v_mfma_f32_16x16x32_bf16 v[100:103], v[216:219], v[156:159], v[100:103]
	v_mfma_f32_16x16x32_bf16 v[96:99], v[232:235], v[156:159], v[96:99]
	v_mfma_f32_16x16x32_bf16 v[84:87], v[216:219], v[164:167], v[84:87]
	v_mfma_f32_16x16x32_bf16 v[80:83], v[232:235], v[164:167], v[80:83]
	v_mfma_f32_16x16x32_bf16 v[68:71], v[216:219], v[208:211], v[68:71]
	v_mfma_f32_16x16x32_bf16 v[64:67], v[232:235], v[208:211], v[64:67]
	v_mfma_f32_16x16x32_bf16 v[116:119], v[220:223], v[152:155], v[116:119]
	v_mfma_f32_16x16x32_bf16 v[112:115], v[240:243], v[152:155], v[112:115]
	v_mfma_f32_16x16x32_bf16 v[100:103], v[220:223], v[160:163], v[100:103]
	v_mfma_f32_16x16x32_bf16 v[96:99], v[240:243], v[160:163], v[96:99]
	v_mfma_f32_16x16x32_bf16 v[84:87], v[220:223], v[204:207], v[84:87]
	v_mfma_f32_16x16x32_bf16 v[80:83], v[240:243], v[204:207], v[80:83]
	v_mfma_f32_16x16x32_bf16 v[68:71], v[220:223], v[212:215], v[68:71]
	v_mfma_f32_16x16x32_bf16 v[64:67], v[240:243], v[212:215], v[64:67]
	s_mov_b32 m0, s19
	v_lshl_add_u64 v[244:245], s[8:9], 0, v[178:179]
	s_barrier
	ds_read_b128 v[148:151], v202 offset:16384
	ds_read_b128 v[152:155], v202 offset:17408
	ds_read_b128 v[156:159], v202 offset:18432
	ds_read_b128 v[160:163], v202 offset:19456
	ds_read_b128 v[164:167], v202 offset:20480
	ds_read_b128 v[204:207], v202 offset:21504
	ds_read_b128 v[208:211], v202 offset:22528
	ds_read_b128 v[212:215], v202 offset:23552
	global_load_lds_dwordx4 v[244:245], off
	s_mov_b32 m0, s21
	v_lshl_add_u64 v[246:247], s[8:9], 0, v[174:175]
	global_load_lds_dwordx4 v[246:247], off
	s_barrier
	s_waitcnt lgkmcnt(0)
	v_mfma_f32_16x16x32_bf16 v[60:63], v[132:135], v[148:151], v[60:63]
	v_mfma_f32_16x16x32_bf16 v[56:59], v[140:143], v[148:151], v[56:59]
	v_mfma_f32_16x16x32_bf16 v[44:47], v[132:135], v[156:159], v[44:47]
	v_mfma_f32_16x16x32_bf16 v[40:43], v[140:143], v[156:159], v[40:43]
	v_mfma_f32_16x16x32_bf16 v[28:31], v[132:135], v[164:167], v[28:31]
	v_mfma_f32_16x16x32_bf16 v[24:27], v[140:143], v[164:167], v[24:27]
	v_mfma_f32_16x16x32_bf16 v[12:15], v[132:135], v[208:211], v[12:15]
	v_mfma_f32_16x16x32_bf16 v[8:11], v[140:143], v[208:211], v[8:11]
	v_mfma_f32_16x16x32_bf16 v[60:63], v[136:139], v[152:155], v[60:63]
	v_mfma_f32_16x16x32_bf16 v[56:59], v[144:147], v[152:155], v[56:59]
	v_mfma_f32_16x16x32_bf16 v[44:47], v[136:139], v[160:163], v[44:47]
	v_mfma_f32_16x16x32_bf16 v[40:43], v[144:147], v[160:163], v[40:43]
	v_mfma_f32_16x16x32_bf16 v[28:31], v[136:139], v[204:207], v[28:31]
	v_mfma_f32_16x16x32_bf16 v[24:27], v[144:147], v[204:207], v[24:27]
	v_mfma_f32_16x16x32_bf16 v[12:15], v[136:139], v[212:215], v[12:15]
	v_mfma_f32_16x16x32_bf16 v[8:11], v[144:147], v[212:215], v[8:11]
	s_barrier
	s_add_u32 s30, s30, s90
	s_addc_u32 s31, s31, s91
	s_add_i32 s46, s53, 0x14000
	s_mov_b32 m0, s46
	v_lshl_add_u64 v[248:249], s[30:31], 0, v[180:181]
	global_load_lds_dwordx4 v[248:249], off
	s_add_i32 m0, s46, 0x2000
	v_lshl_add_u64 v[250:251], s[30:31], 0, v[176:177]
	global_load_lds_dwordx4 v[250:251], off
	s_waitcnt vmcnt(6)
	s_barrier
	v_mfma_f32_16x16x32_bf16 v[52:55], v[216:219], v[148:151], v[52:55]
	v_mfma_f32_16x16x32_bf16 v[48:51], v[232:235], v[148:151], v[48:51]
	v_mfma_f32_16x16x32_bf16 v[36:39], v[216:219], v[156:159], v[36:39]
	v_mfma_f32_16x16x32_bf16 v[32:35], v[232:235], v[156:159], v[32:35]
	v_mfma_f32_16x16x32_bf16 v[20:23], v[216:219], v[164:167], v[20:23]
	v_mfma_f32_16x16x32_bf16 v[16:19], v[232:235], v[164:167], v[16:19]
	v_mfma_f32_16x16x32_bf16 v[4:7], v[216:219], v[208:211], v[4:7]
	v_mfma_f32_16x16x32_bf16 v[0:3], v[232:235], v[208:211], v[0:3]
	v_mfma_f32_16x16x32_bf16 v[52:55], v[220:223], v[152:155], v[52:55]
	v_mfma_f32_16x16x32_bf16 v[48:51], v[240:243], v[152:155], v[48:51]
	v_mfma_f32_16x16x32_bf16 v[36:39], v[220:223], v[160:163], v[36:39]
	v_mfma_f32_16x16x32_bf16 v[32:35], v[240:243], v[160:163], v[32:35]
	v_mfma_f32_16x16x32_bf16 v[20:23], v[220:223], v[204:207], v[20:23]
	v_mfma_f32_16x16x32_bf16 v[16:19], v[240:243], v[204:207], v[16:19]
	v_mfma_f32_16x16x32_bf16 v[4:7], v[220:223], v[212:215], v[4:7]
	v_mfma_f32_16x16x32_bf16 v[0:3], v[240:243], v[212:215], v[0:3]
	s_barrier
	ds_read_b128 v[132:135], v252 offset:32768
	ds_read_b128 v[136:139], v252 offset:33792
	ds_read_b128 v[140:143], v252 offset:34816
	ds_read_b128 v[144:147], v252 offset:35840
	s_add_u32 s8, s8, s22
	s_addc_u32 s9, s9, s23
	s_mov_b32 m0, s64
	v_lshl_add_u64 v[216:217], s[8:9], 0, v[178:179]
	ds_read_b128 v[148:151], v202 offset:32768
	ds_read_b128 v[152:155], v202 offset:33792
	ds_read_b128 v[156:159], v202 offset:34816
	ds_read_b128 v[160:163], v202 offset:35840
	ds_read_b128 v[164:167], v202 offset:36864
	ds_read_b128 v[204:207], v202 offset:37888
	ds_read_b128 v[208:211], v202 offset:38912
	ds_read_b128 v[212:215], v202 offset:39936
	global_load_lds_dwordx4 v[216:217], off
	s_mov_b32 m0, s65
	v_lshl_add_u64 v[216:217], s[8:9], 0, v[174:175]
	global_load_lds_dwordx4 v[216:217], off
	s_waitcnt lgkmcnt(8)
	s_barrier
	s_waitcnt lgkmcnt(0)
	v_mfma_f32_16x16x32_bf16 v[124:127], v[132:135], v[148:151], v[124:127]
	v_mfma_f32_16x16x32_bf16 v[120:123], v[140:143], v[148:151], v[120:123]
	v_mfma_f32_16x16x32_bf16 v[108:111], v[132:135], v[156:159], v[108:111]
	v_mfma_f32_16x16x32_bf16 v[104:107], v[140:143], v[156:159], v[104:107]
	v_mfma_f32_16x16x32_bf16 v[92:95], v[132:135], v[164:167], v[92:95]
	v_mfma_f32_16x16x32_bf16 v[88:91], v[140:143], v[164:167], v[88:91]
	v_mfma_f32_16x16x32_bf16 v[76:79], v[132:135], v[208:211], v[76:79]
	v_mfma_f32_16x16x32_bf16 v[72:75], v[140:143], v[208:211], v[72:75]
	v_mfma_f32_16x16x32_bf16 v[124:127], v[136:139], v[152:155], v[124:127]
	v_mfma_f32_16x16x32_bf16 v[120:123], v[144:147], v[152:155], v[120:123]
	v_mfma_f32_16x16x32_bf16 v[108:111], v[136:139], v[160:163], v[108:111]
	v_mfma_f32_16x16x32_bf16 v[104:107], v[144:147], v[160:163], v[104:107]
	v_mfma_f32_16x16x32_bf16 v[92:95], v[136:139], v[204:207], v[92:95]
	v_mfma_f32_16x16x32_bf16 v[88:91], v[144:147], v[204:207], v[88:91]
	v_mfma_f32_16x16x32_bf16 v[76:79], v[136:139], v[212:215], v[76:79]
	v_mfma_f32_16x16x32_bf16 v[72:75], v[144:147], v[212:215], v[72:75]
	s_barrier
	s_add_i32 s9, s77, s53
	s_add_i32 m0, s9, 0xffffff80
	ds_read_b128 v[216:219], v252 offset:49152
	ds_read_b128 v[220:223], v252 offset:50176
	ds_read_b128 v[232:235], v252 offset:51200
	ds_read_b128 v[240:243], v252 offset:52224
	global_load_lds_dwordx4 v[190:191], off offset:128
	s_add_i32 m0, s9, 0x1f80
	s_nop 0
	global_load_lds_dwordx4 v[224:225], off offset:128
	s_barrier
	s_waitcnt lgkmcnt(0)
	v_mfma_f32_16x16x32_bf16 v[116:119], v[216:219], v[148:151], v[116:119]
	v_mfma_f32_16x16x32_bf16 v[112:115], v[232:235], v[148:151], v[112:115]
	v_mfma_f32_16x16x32_bf16 v[100:103], v[216:219], v[156:159], v[100:103]
	v_mfma_f32_16x16x32_bf16 v[96:99], v[232:235], v[156:159], v[96:99]
	v_mfma_f32_16x16x32_bf16 v[84:87], v[216:219], v[164:167], v[84:87]
	v_mfma_f32_16x16x32_bf16 v[80:83], v[232:235], v[164:167], v[80:83]
	v_mfma_f32_16x16x32_bf16 v[68:71], v[216:219], v[208:211], v[68:71]
	v_mfma_f32_16x16x32_bf16 v[64:67], v[232:235], v[208:211], v[64:67]
	v_mfma_f32_16x16x32_bf16 v[116:119], v[220:223], v[152:155], v[116:119]
	v_mfma_f32_16x16x32_bf16 v[112:115], v[240:243], v[152:155], v[112:115]
	v_mfma_f32_16x16x32_bf16 v[100:103], v[220:223], v[160:163], v[100:103]
	v_mfma_f32_16x16x32_bf16 v[96:99], v[240:243], v[160:163], v[96:99]
	v_mfma_f32_16x16x32_bf16 v[84:87], v[220:223], v[204:207], v[84:87]
	v_mfma_f32_16x16x32_bf16 v[80:83], v[240:243], v[204:207], v[80:83]
	v_mfma_f32_16x16x32_bf16 v[68:71], v[220:223], v[212:215], v[68:71]
	v_mfma_f32_16x16x32_bf16 v[64:67], v[240:243], v[212:215], v[64:67]
	s_add_i32 m0, s66, 0xffffff80
	s_barrier
	ds_read_b128 v[148:151], v202 offset:49152
	ds_read_b128 v[152:155], v202 offset:50176
	ds_read_b128 v[156:159], v202 offset:51200
	ds_read_b128 v[160:163], v202 offset:52224
	ds_read_b128 v[164:167], v202 offset:53248
	ds_read_b128 v[204:207], v202 offset:54272
	ds_read_b128 v[208:211], v202 offset:55296
	ds_read_b128 v[212:215], v202 offset:56320
	global_load_lds_dwordx4 v[244:245], off offset:128
	s_add_i32 m0, s67, 0xffffff80
	s_nop 0
	global_load_lds_dwordx4 v[246:247], off offset:128
	s_barrier
	s_waitcnt lgkmcnt(0)
	v_mfma_f32_16x16x32_bf16 v[60:63], v[132:135], v[148:151], v[60:63]
	v_mfma_f32_16x16x32_bf16 v[56:59], v[140:143], v[148:151], v[56:59]
	v_mfma_f32_16x16x32_bf16 v[44:47], v[132:135], v[156:159], v[44:47]
	v_mfma_f32_16x16x32_bf16 v[40:43], v[140:143], v[156:159], v[40:43]
	v_mfma_f32_16x16x32_bf16 v[28:31], v[132:135], v[164:167], v[28:31]
	v_mfma_f32_16x16x32_bf16 v[24:27], v[140:143], v[164:167], v[24:27]
	v_mfma_f32_16x16x32_bf16 v[12:15], v[132:135], v[208:211], v[12:15]
	v_mfma_f32_16x16x32_bf16 v[8:11], v[140:143], v[208:211], v[8:11]
	v_mfma_f32_16x16x32_bf16 v[60:63], v[136:139], v[152:155], v[60:63]
	v_mfma_f32_16x16x32_bf16 v[56:59], v[144:147], v[152:155], v[56:59]
	v_mfma_f32_16x16x32_bf16 v[44:47], v[136:139], v[160:163], v[44:47]
	v_mfma_f32_16x16x32_bf16 v[40:43], v[144:147], v[160:163], v[40:43]
	v_mfma_f32_16x16x32_bf16 v[28:31], v[136:139], v[204:207], v[28:31]
	v_mfma_f32_16x16x32_bf16 v[24:27], v[144:147], v[204:207], v[24:27]
	v_mfma_f32_16x16x32_bf16 v[12:15], v[136:139], v[212:215], v[12:15]
	v_mfma_f32_16x16x32_bf16 v[8:11], v[144:147], v[212:215], v[8:11]
	s_barrier
	s_add_i32 s8, s53, 0x1c000
	s_add_i32 m0, s8, 0xffffff80
	s_nop 0
	global_load_lds_dwordx4 v[248:249], off offset:128
	s_add_i32 m0, s8, 0x1f80
	s_nop 0
	global_load_lds_dwordx4 v[250:251], off offset:128
	s_waitcnt vmcnt(6)
	s_barrier
	v_mfma_f32_16x16x32_bf16 v[52:55], v[216:219], v[148:151], v[52:55]
	v_mfma_f32_16x16x32_bf16 v[48:51], v[232:235], v[148:151], v[48:51]
	v_mfma_f32_16x16x32_bf16 v[36:39], v[216:219], v[156:159], v[36:39]
	v_mfma_f32_16x16x32_bf16 v[32:35], v[232:235], v[156:159], v[32:35]
	v_mfma_f32_16x16x32_bf16 v[20:23], v[216:219], v[164:167], v[20:23]
	v_mfma_f32_16x16x32_bf16 v[16:19], v[232:235], v[164:167], v[16:19]
	v_mfma_f32_16x16x32_bf16 v[4:7], v[216:219], v[208:211], v[4:7]
	v_mfma_f32_16x16x32_bf16 v[0:3], v[232:235], v[208:211], v[0:3]
	v_mfma_f32_16x16x32_bf16 v[52:55], v[220:223], v[152:155], v[52:55]
	v_mfma_f32_16x16x32_bf16 v[48:51], v[240:243], v[152:155], v[48:51]
	v_mfma_f32_16x16x32_bf16 v[36:39], v[220:223], v[160:163], v[36:39]
	v_mfma_f32_16x16x32_bf16 v[32:35], v[240:243], v[160:163], v[32:35]
	v_mfma_f32_16x16x32_bf16 v[20:23], v[220:223], v[204:207], v[20:23]
	v_mfma_f32_16x16x32_bf16 v[16:19], v[240:243], v[204:207], v[16:19]
	v_mfma_f32_16x16x32_bf16 v[4:7], v[220:223], v[212:215], v[4:7]
	v_mfma_f32_16x16x32_bf16 v[0:3], v[240:243], v[212:215], v[0:3]
	s_add_u32 s4, s4, 0x100
	s_addc_u32 s5, s5, 0
	s_cmp_ge_i32 s38, s68
	s_barrier
	s_cbranch_scc1 .Lkx_exit
	s_mov_b32 s46, s38
	s_andn2_b64 vcc, exec, s[96:97]
	s_cbranch_vccnz .LBB0_760
	s_branch .LBB0_754
